# phase 0 adaLN GEMV: 8 weight-row loads per iteration issued together with counted vmcnt instead of one at a time
# speedup vs baseline: 1.0043x; 1.0043x over previous
.LBB0_447:
	v_lshl_add_u64 v[44:45], v[42:43], 0, s[58:59]
	global_load_dwordx4 v[136:139], v[44:45], off
	v_add_co_u32_e32 v168, vcc, s72, v44
	s_nop 1
	v_addc_co_u32_e32 v169, vcc, 0, v45, vcc
	global_load_dwordx4 v[140:143], v[168:169], off
	v_add_co_u32_e32 v170, vcc, 0xc000, v44
	s_nop 1
	v_addc_co_u32_e32 v171, vcc, 0, v45, vcc
	global_load_dwordx4 v[144:147], v[170:171], off
	v_add_co_u32_e32 v172, vcc, 0x12000, v44
	s_nop 1
	v_addc_co_u32_e32 v173, vcc, 0, v45, vcc
	global_load_dwordx4 v[148:151], v[172:173], off
	v_add_co_u32_e32 v174, vcc, s69, v44
	s_nop 1
	v_addc_co_u32_e32 v175, vcc, 0, v45, vcc
	global_load_dwordx4 v[152:155], v[174:175], off
	v_add_co_u32_e32 v176, vcc, 0x1e000, v44
	s_nop 1
	v_addc_co_u32_e32 v177, vcc, 0, v45, vcc
	global_load_dwordx4 v[156:159], v[176:177], off
	v_add_co_u32_e32 v178, vcc, 0x24000, v44
	s_nop 1
	v_addc_co_u32_e32 v179, vcc, 0, v45, vcc
	global_load_dwordx4 v[160:163], v[178:179], off
	v_add_co_u32_e32 v180, vcc, 0x2a000, v44
	s_nop 1
	v_addc_co_u32_e32 v181, vcc, 0, v45, vcc
	global_load_dwordx4 v[164:167], v[180:181], off
	ds_read_b128 v[56:59], v37
	ds_read_b128 v[20:23], v37 offset:16
	ds_read_b128 v[60:63], v37 offset:4096
	ds_read_b128 v[64:67], v37 offset:8192
	ds_read_b128 v[68:71], v37 offset:12288
	ds_read_b128 v[72:75], v37 offset:16384
	s_mov_b32 s26, 0xc000
	s_add_u32 s58, s58, 0x30000
	s_addc_u32 s59, s59, 0
	s_cmp_eq_u32 s58, 0x180000
	s_waitcnt vmcnt(7) lgkmcnt(5)
	v_pk_fma_f32 v[80:81], v[136:137], v[56:57], v[0:1] op_sel_hi:[1,0,1]
	v_pk_fma_f32 v[82:83], v[138:139], v[56:57], v[2:3] op_sel_hi:[1,0,1]
	s_waitcnt lgkmcnt(3)
	v_pk_fma_f32 v[16:17], v[136:137], v[60:61], v[16:17] op_sel_hi:[1,0,1]
	s_waitcnt lgkmcnt(2)
	v_pk_fma_f32 v[12:13], v[136:137], v[64:65], v[12:13] op_sel_hi:[1,0,1]
	s_waitcnt lgkmcnt(1)
	v_pk_fma_f32 v[8:9], v[136:137], v[68:69], v[8:9] op_sel_hi:[1,0,1]
	s_waitcnt lgkmcnt(0)
	v_pk_fma_f32 v[4:5], v[136:137], v[72:73], v[4:5] op_sel_hi:[1,0,1]
	v_pk_fma_f32 v[18:19], v[138:139], v[60:61], v[18:19] op_sel_hi:[1,0,1]
	v_pk_fma_f32 v[14:15], v[138:139], v[64:65], v[14:15] op_sel_hi:[1,0,1]
	v_pk_fma_f32 v[10:11], v[138:139], v[68:69], v[10:11] op_sel_hi:[1,0,1]
	v_pk_fma_f32 v[6:7], v[138:139], v[72:73], v[6:7] op_sel_hi:[1,0,1]
	s_waitcnt vmcnt(6)
	v_pk_fma_f32 v[76:77], v[140:141], v[56:57], v[80:81] op_sel:[0,1,0]
	v_pk_fma_f32 v[16:17], v[140:141], v[60:61], v[16:17] op_sel:[0,1,0]
	v_pk_fma_f32 v[12:13], v[140:141], v[64:65], v[12:13] op_sel:[0,1,0]
	v_pk_fma_f32 v[8:9], v[140:141], v[68:69], v[8:9] op_sel:[0,1,0]
	v_pk_fma_f32 v[4:5], v[140:141], v[72:73], v[4:5] op_sel:[0,1,0]
	v_pk_fma_f32 v[56:57], v[142:143], v[56:57], v[82:83] op_sel:[0,1,0]
	v_pk_fma_f32 v[18:19], v[142:143], v[60:61], v[18:19] op_sel:[0,1,0]
	v_pk_fma_f32 v[14:15], v[142:143], v[64:65], v[14:15] op_sel:[0,1,0]
	v_pk_fma_f32 v[10:11], v[142:143], v[68:69], v[10:11] op_sel:[0,1,0]
	v_pk_fma_f32 v[6:7], v[142:143], v[72:73], v[6:7] op_sel:[0,1,0]
	s_mov_b32 s26, 0x12000
	s_waitcnt vmcnt(5)
	v_pk_fma_f32 v[60:61], v[144:145], v[58:59], v[76:77] op_sel_hi:[1,0,1]
	v_pk_fma_f32 v[16:17], v[144:145], v[62:63], v[16:17] op_sel_hi:[1,0,1]
	v_pk_fma_f32 v[12:13], v[144:145], v[66:67], v[12:13] op_sel_hi:[1,0,1]
	v_pk_fma_f32 v[8:9], v[144:145], v[70:71], v[8:9] op_sel_hi:[1,0,1]
	v_pk_fma_f32 v[4:5], v[144:145], v[74:75], v[4:5] op_sel_hi:[1,0,1]
	v_pk_fma_f32 v[56:57], v[146:147], v[58:59], v[56:57] op_sel_hi:[1,0,1]
	v_pk_fma_f32 v[18:19], v[146:147], v[62:63], v[18:19] op_sel_hi:[1,0,1]
	v_pk_fma_f32 v[14:15], v[146:147], v[66:67], v[14:15] op_sel_hi:[1,0,1]
	v_pk_fma_f32 v[10:11], v[146:147], v[70:71], v[10:11] op_sel_hi:[1,0,1]
	v_pk_fma_f32 v[6:7], v[146:147], v[74:75], v[6:7] op_sel_hi:[1,0,1]
	v_mov_b32_e32 v58, v59
	s_mov_b32 s26, 0x1e000
	s_waitcnt vmcnt(4)
	v_pk_fma_f32 v[68:69], v[150:151], v[58:59], v[56:57] op_sel_hi:[1,0,1]
	v_mov_b32_e32 v56, v63
	v_pk_fma_f32 v[16:17], v[148:149], v[56:57], v[16:17] op_sel_hi:[1,0,1]
	v_pk_fma_f32 v[18:19], v[150:151], v[56:57], v[18:19] op_sel_hi:[1,0,1]
	v_mov_b32_e32 v56, v67
	v_pk_fma_f32 v[66:67], v[148:149], v[56:57], v[12:13] op_sel_hi:[1,0,1]
	v_mov_b32_e32 v12, v71
	v_pk_fma_f32 v[72:73], v[150:151], v[12:13], v[10:11] op_sel_hi:[1,0,1]
	v_pk_fma_f32 v[70:71], v[148:149], v[12:13], v[8:9] op_sel_hi:[1,0,1]
	v_mov_b32_e32 v8, v75
	v_pk_fma_f32 v[64:65], v[148:149], v[58:59], v[60:61] op_sel_hi:[1,0,1]
	v_pk_fma_f32 v[14:15], v[150:151], v[56:57], v[14:15] op_sel_hi:[1,0,1]
	v_pk_fma_f32 v[0:1], v[148:149], v[8:9], v[4:5] op_sel_hi:[1,0,1]
	v_pk_fma_f32 v[74:75], v[150:151], v[8:9], v[6:7] op_sel_hi:[1,0,1]
	ds_read_b128 v[2:5], v37 offset:4112
	ds_read_b128 v[6:9], v37 offset:8208
	ds_read_b128 v[56:59], v37 offset:12304
	ds_read_b128 v[60:63], v37 offset:16400
	v_add_u32_e32 v37, 32, v37
	s_waitcnt vmcnt(3)
	v_pk_fma_f32 v[64:65], v[152:153], v[20:21], v[64:65] op_sel_hi:[1,0,1]
	s_waitcnt lgkmcnt(3)
	v_pk_fma_f32 v[16:17], v[152:153], v[2:3], v[16:17] op_sel_hi:[1,0,1]
	s_waitcnt lgkmcnt(2)
	v_pk_fma_f32 v[66:67], v[152:153], v[6:7], v[66:67] op_sel_hi:[1,0,1]
	s_waitcnt lgkmcnt(1)
	v_pk_fma_f32 v[70:71], v[152:153], v[56:57], v[70:71] op_sel_hi:[1,0,1]
	s_waitcnt lgkmcnt(0)
	v_pk_fma_f32 v[0:1], v[152:153], v[60:61], v[0:1] op_sel_hi:[1,0,1]
	v_pk_fma_f32 v[68:69], v[154:155], v[20:21], v[68:69] op_sel_hi:[1,0,1]
	v_pk_fma_f32 v[18:19], v[154:155], v[2:3], v[18:19] op_sel_hi:[1,0,1]
	v_pk_fma_f32 v[14:15], v[154:155], v[6:7], v[14:15] op_sel_hi:[1,0,1]
	v_pk_fma_f32 v[72:73], v[154:155], v[56:57], v[72:73] op_sel_hi:[1,0,1]
	v_pk_fma_f32 v[74:75], v[154:155], v[60:61], v[74:75] op_sel_hi:[1,0,1]
	s_mov_b32 s26, 0x24000
	s_waitcnt vmcnt(2)
	v_pk_fma_f32 v[64:65], v[156:157], v[20:21], v[64:65] op_sel:[0,1,0]
	v_pk_fma_f32 v[16:17], v[156:157], v[2:3], v[16:17] op_sel:[0,1,0]
	v_pk_fma_f32 v[66:67], v[156:157], v[6:7], v[66:67] op_sel:[0,1,0]
	v_pk_fma_f32 v[6:7], v[158:159], v[6:7], v[14:15] op_sel:[0,1,0]
	v_pk_fma_f32 v[14:15], v[156:157], v[56:57], v[70:71] op_sel:[0,1,0]
	v_pk_fma_f32 v[10:11], v[156:157], v[60:61], v[0:1] op_sel:[0,1,0]
	v_pk_fma_f32 v[18:19], v[158:159], v[2:3], v[18:19] op_sel:[0,1,0]
	s_mov_b32 s26, 0x2a000
	v_pk_fma_f32 v[20:21], v[158:159], v[20:21], v[68:69] op_sel:[0,1,0]
	v_pk_fma_f32 v[56:57], v[158:159], v[56:57], v[72:73] op_sel:[0,1,0]
	v_pk_fma_f32 v[12:13], v[158:159], v[60:61], v[74:75] op_sel:[0,1,0]
	s_waitcnt vmcnt(1)
	v_pk_fma_f32 v[60:61], v[160:161], v[22:23], v[64:65] op_sel_hi:[1,0,1]
	v_pk_fma_f32 v[16:17], v[160:161], v[4:5], v[16:17] op_sel_hi:[1,0,1]
	v_pk_fma_f32 v[68:69], v[160:161], v[8:9], v[66:67] op_sel_hi:[1,0,1]
	v_pk_fma_f32 v[70:71], v[160:161], v[58:59], v[14:15] op_sel_hi:[1,0,1]
	v_pk_fma_f32 v[72:73], v[160:161], v[62:63], v[10:11] op_sel_hi:[1,0,1]
	v_pk_fma_f32 v[18:19], v[162:163], v[4:5], v[18:19] op_sel_hi:[1,0,1]
	v_mov_b32_e32 v4, v5
	v_pk_fma_f32 v[6:7], v[162:163], v[8:9], v[6:7] op_sel_hi:[1,0,1]
	v_pk_fma_f32 v[20:21], v[162:163], v[22:23], v[20:21] op_sel_hi:[1,0,1]
	v_pk_fma_f32 v[56:57], v[162:163], v[58:59], v[56:57] op_sel_hi:[1,0,1]
	v_pk_fma_f32 v[74:75], v[162:163], v[62:63], v[12:13] op_sel_hi:[1,0,1]
	v_mov_b32_e32 v2, v23
	s_waitcnt vmcnt(0)
	v_pk_fma_f32 v[16:17], v[164:165], v[4:5], v[16:17] op_sel_hi:[1,0,1]
	v_pk_fma_f32 v[18:19], v[166:167], v[4:5], v[18:19] op_sel_hi:[1,0,1]
	v_mov_b32_e32 v4, v9
	v_pk_fma_f32 v[12:13], v[164:165], v[4:5], v[68:69] op_sel_hi:[1,0,1]
	v_pk_fma_f32 v[14:15], v[166:167], v[4:5], v[6:7] op_sel_hi:[1,0,1]
	v_mov_b32_e32 v4, v59
	v_mov_b32_e32 v6, v63
	v_pk_fma_f32 v[0:1], v[164:165], v[2:3], v[60:61] op_sel_hi:[1,0,1]
	v_pk_fma_f32 v[2:3], v[166:167], v[2:3], v[20:21] op_sel_hi:[1,0,1]
	v_pk_fma_f32 v[8:9], v[164:165], v[4:5], v[70:71] op_sel_hi:[1,0,1]
	v_pk_fma_f32 v[10:11], v[166:167], v[4:5], v[56:57] op_sel_hi:[1,0,1]
	v_pk_fma_f32 v[4:5], v[164:165], v[6:7], v[72:73] op_sel_hi:[1,0,1]
	v_pk_fma_f32 v[6:7], v[166:167], v[6:7], v[74:75] op_sel_hi:[1,0,1]
	s_cbranch_scc0 .LBB0_447
	ds_write_b128 v48, v[0:3] offset:20480
	ds_write_b128 v48, v[16:19] offset:20736
	ds_write_b128 v48, v[12:15] offset:20992
	ds_write_b128 v48, v[8:11] offset:21248
	ds_write_b128 v48, v[4:7] offset:21504
	s_waitcnt lgkmcnt(0)
	s_barrier
	s_and_saveexec_b64 s[58:59], s[88:89]
	v_readlane_b32 s62, v251, 11
	v_readlane_b32 s63, v251, 12
	s_cbranch_execz .LBB0_451
	s_mul_i32 s26, s27, 0x1800
	s_add_i32 s26, s26, s56
	v_or_b32_e32 v0, s26, v49
	v_readlane_b32 s36, v252, 39
	v_ashrrev_i32_e32 v1, 31, v0
	v_readlane_b32 s40, v252, 43
	v_readlane_b32 s41, v252, 44
	s_mul_i32 s27, s27, 5
	v_or_b32_e32 v2, s56, v49
	v_lshl_add_u64 v[0:1], v[0:1], 2, s[40:41]
	s_mov_b64 s[56:57], 0
	v_mov_b32_e32 v3, v24
	v_readlane_b32 s37, v252, 40
	v_readlane_b32 s38, v252, 41
	v_readlane_b32 s39, v252, 42
	v_readlane_b32 s42, v252, 45
	v_readlane_b32 s43, v252, 46
	v_readlane_b32 s44, v252, 47
	v_readlane_b32 s45, v252, 48
	v_readlane_b32 s46, v252, 49
	v_readlane_b32 s47, v252, 50
	v_readlane_b32 s48, v252, 51
	v_readlane_b32 s49, v252, 52
	v_readlane_b32 s50, v252, 53
	v_readlane_b32 s51, v252, 54
